# EpiResid XB stores with the nt hint (streaming: the tile is next read after a grid barrier by other CUs)
# baseline (speedup 1.0000x reference)
; __device__ __forceinline__ float bf_lo(unsigned u) { return __uint_as_float(u << 16); }
; __device__ __forceinline__ float bf_hi(unsigned u) { return __uint_as_float(u & 0xffff0000u); }
; __device__ __forceinline__ unsigned pk_bf16(float lo, float hi) { const f32x2 v = {lo, hi}; const bf16x2_t b = __builtin_convertvector(v, bf16x2_t); return __builtin_bit_cast(unsigned, b); }
;     __device__ __forceinline__ void operator()(const f32x4 (&acc)[2][2][4][2], const pg8::Unit& u, int wr, int wc, int fr, int fq) const {
;         asm volatile("" : "+v"(fr));
;         const int row0 = u.pm * 256 + wr * 64 + fr, col0 = u.pn * 256 + wc * 32 + 4 * fq;
;         const bool rf32 = (rp != nullptr) && (u.pm < MP / 256);
; #pragma unroll
;         for (int ai = 0; ai < 2; ++ai)
; #pragma unroll
;             for (int m = 0; m < 4; ++m) {
;                 const int row = row0 + ai * 128 + m * 16; const size_t off = (size_t)row * DM + col0; float q = 0.f;
;                 f32x4 r4[2][2];
;                 if (rf32) {
; #pragma unroll
;                     for (int bj = 0; bj < 2; ++bj)
; #pragma unroll
;                         for (int n = 0; n < 2; ++n) r4[bj][n] = *(const f32x4*)(rp + off + bj * 128 + n * 16);
;                 } else {
; #pragma unroll
;                     for (int bj = 0; bj < 2; ++bj)
; #pragma unroll
;                         for (int n = 0; n < 2; ++n) { const u32x2 w = *(const u32x2*)(XB + off + bj * 128 + n * 16); r4[bj][n] = (f32x4){bf_lo(w.x), bf_hi(w.x), bf_lo(w.y), bf_hi(w.y)}; }
;                 }
; #pragma unroll
;                 for (int bj = 0; bj < 2; ++bj)
; #pragma unroll
;                     for (int n = 0; n < 2; ++n) { const f32x4 x4 = r4[bj][n] + acc[ai][bj][m][n];
;                         q += (x4[0] * x4[0] + x4[1] * x4[1]) + (x4[2] * x4[2] + x4[3] * x4[3]);
;                         u32x2 w; w.x = pk_bf16(x4[0], x4[1]); w.y = pk_bf16(x4[2], x4[3]); *(u32x2*)(XB + off + bj * 128 + n * 16) = w; }
;                 q += __shfl_xor(q, 16); q += __shfl_xor(q, 32);
;                 if (fq == 0) ssq[(size_t)row * 16 + u.pn * 4 + wc] = q;
;                 if (m & 1) asm volatile("" ::: "memory");
;             }
.LBB0_1683:
	s_lshl_b32 s4, s51, 8
	v_mov_b32_e32 v158, v1
	s_add_i32 s4, s4, s46
	s_lshl_b32 s28, s50, 2
	v_add_u32_e32 v160, s4, v158
	v_ashrrev_i32_e32 v161, 31, v160
	v_lshl_or_b32 v158, s50, 8, v163
	v_lshlrev_b64 v[166:167], 11, v[160:161]
	v_ashrrev_i32_e32 v159, 31, v158
	v_lshl_add_u64 v[166:167], s[14:15], 0, v[166:167]
	v_lshl_add_u64 v[166:167], v[158:159], 1, v[166:167]
	s_ashr_i32 s29, s28, 31
	v_lshlrev_b32_e32 v252, 11, v160
	v_lshl_add_u32 v252, v158, 1, v252
	v_bfe_u32 v253, v190, 4, 1
	v_mul_u32_u24_e32 v253, 24, v253
	v_add_u32_e32 v252, v252, v253
	s_lshl_b32 s88, s45, 2
	v_lshl_add_u32 v189, v160, 6, s88
	v_lshl_add_u32 v189, s28, 2, v189
	global_load_dwordx4 v[204:207], v252, s[14:15]
	global_load_dwordx4 v[208:211], v252, s[14:15] offset:256
	v_add_u32_e32 v253, 0x8000, v252
	global_load_dwordx4 v[212:215], v253, s[14:15]
	global_load_dwordx4 v[216:219], v253, s[14:15] offset:256
	v_add_u32_e32 v253, 0x10000, v252
	global_load_dwordx4 v[220:223], v253, s[14:15]
	global_load_dwordx4 v[224:227], v253, s[14:15] offset:256
	v_add_u32_e32 v253, 0x18000, v252
	global_load_dwordx4 v[228:231], v253, s[14:15]
	global_load_dwordx4 v[232:235], v253, s[14:15] offset:256
	v_add_u32_e32 v253, 0x40000, v252
	global_load_dwordx4 v[236:239], v253, s[14:15]
	global_load_dwordx4 v[240:243], v253, s[14:15] offset:256
	v_add_u32_e32 v253, 0x48000, v252
	global_load_dwordx4 v[244:247], v253, s[14:15]
	global_load_dwordx4 v[248:251], v253, s[14:15] offset:256
	s_waitcnt vmcnt(10)
	v_permlane16_swap_b32_e32 v204, v206
	v_permlane16_swap_b32_e32 v205, v207
	v_permlane16_swap_b32_e32 v208, v210
	v_permlane16_swap_b32_e32 v209, v211
	v_lshlrev_b32_e32 v166, 16, v204
	v_and_b32_e32 v167, 0xffff0000, v204
	v_lshlrev_b32_e32 v168, 16, v205
	v_and_b32_e32 v169, 0xffff0000, v205
	v_lshlrev_b32_e32 v170, 16, v206
	v_and_b32_e32 v171, 0xffff0000, v206
	v_lshlrev_b32_e32 v172, 16, v207
	v_and_b32_e32 v173, 0xffff0000, v207
	v_lshlrev_b32_e32 v174, 16, v208
	v_and_b32_e32 v175, 0xffff0000, v208
	v_lshlrev_b32_e32 v176, 16, v209
	v_and_b32_e32 v177, 0xffff0000, v209
	v_lshlrev_b32_e32 v178, 16, v210
	v_and_b32_e32 v179, 0xffff0000, v210
	v_lshlrev_b32_e32 v180, 16, v211
	v_and_b32_e32 v181, 0xffff0000, v211
	v_pk_add_f32 v[126:127], v[126:127], v[166:167]
	v_pk_add_f32 v[128:129], v[128:129], v[168:169]
	v_pk_add_f32 v[122:123], v[122:123], v[170:171]
	v_pk_add_f32 v[124:125], v[124:125], v[172:173]
	v_pk_add_f32 v[118:119], v[118:119], v[174:175]
	v_pk_add_f32 v[120:121], v[120:121], v[176:177]
	v_pk_add_f32 v[114:115], v[114:115], v[178:179]
	v_pk_add_f32 v[116:117], v[116:117], v[180:181]
	v_add_u32_e32 v253, 0x50000, v252
	global_load_dwordx4 v[204:207], v253, s[14:15]
	global_load_dwordx4 v[208:211], v253, s[14:15] offset:256
	v_cvt_pk_bf16_f32 v166, v126, v127
	v_cvt_pk_bf16_f32 v167, v128, v129
	v_cvt_pk_bf16_f32 v168, v122, v123
	v_cvt_pk_bf16_f32 v169, v124, v125
	v_cvt_pk_bf16_f32 v170, v118, v119
	v_cvt_pk_bf16_f32 v171, v120, v121
	v_cvt_pk_bf16_f32 v172, v114, v115
	v_cvt_pk_bf16_f32 v173, v116, v117
	v_mul_f32_e32 v174, v126, v126
	v_mul_f32_e32 v175, v122, v122
	v_mul_f32_e32 v176, v118, v118
	v_mul_f32_e32 v177, v114, v114
	v_fmac_f32_e32 v174, v127, v127
	v_fmac_f32_e32 v175, v123, v123
	v_fmac_f32_e32 v176, v119, v119
	v_fmac_f32_e32 v177, v115, v115
	v_fmac_f32_e32 v174, v128, v128
	v_fmac_f32_e32 v175, v124, v124
	v_fmac_f32_e32 v176, v120, v120
	v_fmac_f32_e32 v177, v116, v116
	v_fmac_f32_e32 v174, v129, v129
	v_fmac_f32_e32 v175, v125, v125
	v_fmac_f32_e32 v176, v121, v121
	v_fmac_f32_e32 v177, v117, v117
	v_add_f32_e32 v174, v174, v175
	v_add_f32_e32 v176, v176, v177
	v_add_f32_e32 v178, v174, v176
	ds_bpermute_b32 v179, v131, v178
	v_permlane16_swap_b32_e32 v166, v168
	v_permlane16_swap_b32_e32 v167, v169
	v_permlane16_swap_b32_e32 v170, v172
	v_permlane16_swap_b32_e32 v171, v173
	global_store_dwordx4 v252, v[166:169], s[14:15] nt
	global_store_dwordx4 v252, v[170:173], s[14:15] offset:256 nt
	s_waitcnt lgkmcnt(0)
	v_add_f32_e32 v178, v178, v179
	ds_bpermute_b32 v179, v135, v178
	s_waitcnt lgkmcnt(0)
	v_add_f32_e32 v178, v178, v179
	s_and_saveexec_b64 s[30:31], s[8:9]
	global_store_dword v189, v178, s[16:17]
	s_or_b64 exec, exec, s[30:31]
	s_waitcnt vmcnt(12)
	v_permlane16_swap_b32_e32 v212, v214
	v_permlane16_swap_b32_e32 v213, v215
	v_permlane16_swap_b32_e32 v216, v218
	v_permlane16_swap_b32_e32 v217, v219
	v_lshlrev_b32_e32 v166, 16, v212
	v_and_b32_e32 v167, 0xffff0000, v212
	v_lshlrev_b32_e32 v168, 16, v213
	v_and_b32_e32 v169, 0xffff0000, v213
	v_lshlrev_b32_e32 v170, 16, v214
	v_and_b32_e32 v171, 0xffff0000, v214
	v_lshlrev_b32_e32 v172, 16, v215
	v_and_b32_e32 v173, 0xffff0000, v215
	v_lshlrev_b32_e32 v174, 16, v216
	v_and_b32_e32 v175, 0xffff0000, v216
	v_lshlrev_b32_e32 v176, 16, v217
	v_and_b32_e32 v177, 0xffff0000, v217
	v_lshlrev_b32_e32 v178, 16, v218
	v_and_b32_e32 v179, 0xffff0000, v218
	v_lshlrev_b32_e32 v180, 16, v219
	v_and_b32_e32 v181, 0xffff0000, v219
	v_pk_add_f32 v[110:111], v[110:111], v[166:167]
	v_pk_add_f32 v[112:113], v[112:113], v[168:169]
	v_pk_add_f32 v[106:107], v[106:107], v[170:171]
	v_pk_add_f32 v[108:109], v[108:109], v[172:173]
	v_pk_add_f32 v[102:103], v[102:103], v[174:175]
	v_pk_add_f32 v[104:105], v[104:105], v[176:177]
	v_pk_add_f32 v[98:99], v[98:99], v[178:179]
	v_pk_add_f32 v[100:101], v[100:101], v[180:181]
	v_add_u32_e32 v253, 0x58000, v252
	global_load_dwordx4 v[212:215], v253, s[14:15]
	global_load_dwordx4 v[216:219], v253, s[14:15] offset:256
	v_cvt_pk_bf16_f32 v166, v110, v111
	v_cvt_pk_bf16_f32 v167, v112, v113
	v_cvt_pk_bf16_f32 v168, v106, v107
	v_cvt_pk_bf16_f32 v169, v108, v109
	v_cvt_pk_bf16_f32 v170, v102, v103
	v_cvt_pk_bf16_f32 v171, v104, v105
	v_cvt_pk_bf16_f32 v172, v98, v99
	v_cvt_pk_bf16_f32 v173, v100, v101
	v_mul_f32_e32 v174, v110, v110
	v_mul_f32_e32 v175, v106, v106
	v_mul_f32_e32 v176, v102, v102
	v_mul_f32_e32 v177, v98, v98
	v_fmac_f32_e32 v174, v111, v111
	v_fmac_f32_e32 v175, v107, v107
	v_fmac_f32_e32 v176, v103, v103
	v_fmac_f32_e32 v177, v99, v99
	v_fmac_f32_e32 v174, v112, v112
	v_fmac_f32_e32 v175, v108, v108
	v_fmac_f32_e32 v176, v104, v104
	v_fmac_f32_e32 v177, v100, v100
	v_fmac_f32_e32 v174, v113, v113
	v_fmac_f32_e32 v175, v109, v109
	v_fmac_f32_e32 v176, v105, v105
	v_fmac_f32_e32 v177, v101, v101
	v_add_f32_e32 v174, v174, v175
	v_add_f32_e32 v176, v176, v177
	v_add_f32_e32 v178, v174, v176
	ds_bpermute_b32 v179, v131, v178
	v_permlane16_swap_b32_e32 v166, v168
	v_permlane16_swap_b32_e32 v167, v169
	v_permlane16_swap_b32_e32 v170, v172
	v_permlane16_swap_b32_e32 v171, v173
	v_add_u32_e32 v253, 0x8000, v252
	global_store_dwordx4 v253, v[166:169], s[14:15] nt
	global_store_dwordx4 v253, v[170:173], s[14:15] offset:256 nt
	s_waitcnt lgkmcnt(0)
; __device__ __forceinline__ float bf_lo(unsigned u) { return __uint_as_float(u << 16); }
; __device__ __forceinline__ float bf_hi(unsigned u) { return __uint_as_float(u & 0xffff0000u); }
; __device__ __forceinline__ unsigned pk_bf16(float lo, float hi) { const f32x2 v = {lo, hi}; const bf16x2_t b = __builtin_convertvector(v, bf16x2_t); return __builtin_bit_cast(unsigned, b); }
;     __device__ __forceinline__ void operator()(const f32x4 (&acc)[2][2][4][2], const pg8::Unit& u, int wr, int wc, int fr, int fq) const {
;     ...
;                 const int row = row0 + ai * 128 + m * 16; const size_t off = (size_t)row * DM + col0; float q = 0.f;
;                 f32x4 r4[2][2];
;                 if (rf32) {
; #pragma unroll
;                     for (int bj = 0; bj < 2; ++bj)
; #pragma unroll
;                         for (int n = 0; n < 2; ++n) r4[bj][n] = *(const f32x4*)(rp + off + bj * 128 + n * 16);
;                 } else {
; #pragma unroll
;                     for (int bj = 0; bj < 2; ++bj)
; #pragma unroll
;                         for (int n = 0; n < 2; ++n) { const u32x2 w = *(const u32x2*)(XB + off + bj * 128 + n * 16); r4[bj][n] = (f32x4){bf_lo(w.x), bf_hi(w.x), bf_lo(w.y), bf_hi(w.y)}; }
;                 }
; #pragma unroll
;                 for (int bj = 0; bj < 2; ++bj)
; #pragma unroll
;                     for (int n = 0; n < 2; ++n) { const f32x4 x4 = r4[bj][n] + acc[ai][bj][m][n];
;                         q += (x4[0] * x4[0] + x4[1] * x4[1]) + (x4[2] * x4[2] + x4[3] * x4[3]);
;                         u32x2 w; w.x = pk_bf16(x4[0], x4[1]); w.y = pk_bf16(x4[2], x4[3]); *(u32x2*)(XB + off + bj * 128 + n * 16) = w; }
;                 q += __shfl_xor(q, 16); q += __shfl_xor(q, 32);
;                 if (fq == 0) ssq[(size_t)row * 16 + u.pn * 4 + wc] = q;
;                 if (m & 1) asm volatile("" ::: "memory");
;             }
	v_add_f32_e32 v178, v178, v179
	ds_bpermute_b32 v179, v135, v178
	s_waitcnt lgkmcnt(0)
	v_add_f32_e32 v178, v178, v179
	s_and_saveexec_b64 s[30:31], s[8:9]
	global_store_dword v189, v178, s[16:17] offset:1024
	s_or_b64 exec, exec, s[30:31]
	s_waitcnt vmcnt(14)
	v_permlane16_swap_b32_e32 v220, v222
	v_permlane16_swap_b32_e32 v221, v223
	v_permlane16_swap_b32_e32 v224, v226
	v_permlane16_swap_b32_e32 v225, v227
	v_lshlrev_b32_e32 v166, 16, v220
	v_and_b32_e32 v167, 0xffff0000, v220
	v_lshlrev_b32_e32 v168, 16, v221
	v_and_b32_e32 v169, 0xffff0000, v221
	v_lshlrev_b32_e32 v170, 16, v222
	v_and_b32_e32 v171, 0xffff0000, v222
	v_lshlrev_b32_e32 v172, 16, v223
	v_and_b32_e32 v173, 0xffff0000, v223
	v_lshlrev_b32_e32 v174, 16, v224
	v_and_b32_e32 v175, 0xffff0000, v224
	v_lshlrev_b32_e32 v176, 16, v225
	v_and_b32_e32 v177, 0xffff0000, v225
	v_lshlrev_b32_e32 v178, 16, v226
	v_and_b32_e32 v179, 0xffff0000, v226
	v_lshlrev_b32_e32 v180, 16, v227
	v_and_b32_e32 v181, 0xffff0000, v227
	v_pk_add_f32 v[94:95], v[94:95], v[166:167]
	v_pk_add_f32 v[96:97], v[96:97], v[168:169]
	v_pk_add_f32 v[90:91], v[90:91], v[170:171]
	v_pk_add_f32 v[92:93], v[92:93], v[172:173]
	v_pk_add_f32 v[86:87], v[86:87], v[174:175]
	v_pk_add_f32 v[88:89], v[88:89], v[176:177]
	v_pk_add_f32 v[82:83], v[82:83], v[178:179]
	v_pk_add_f32 v[84:85], v[84:85], v[180:181]
	v_cvt_pk_bf16_f32 v166, v94, v95
	v_cvt_pk_bf16_f32 v167, v96, v97
	v_cvt_pk_bf16_f32 v168, v90, v91
	v_cvt_pk_bf16_f32 v169, v92, v93
	v_cvt_pk_bf16_f32 v170, v86, v87
	v_cvt_pk_bf16_f32 v171, v88, v89
	v_cvt_pk_bf16_f32 v172, v82, v83
	v_cvt_pk_bf16_f32 v173, v84, v85
	v_mul_f32_e32 v174, v94, v94
	v_mul_f32_e32 v175, v90, v90
	v_mul_f32_e32 v176, v86, v86
	v_mul_f32_e32 v177, v82, v82
	v_fmac_f32_e32 v174, v95, v95
	v_fmac_f32_e32 v175, v91, v91
	v_fmac_f32_e32 v176, v87, v87
	v_fmac_f32_e32 v177, v83, v83
	v_fmac_f32_e32 v174, v96, v96
	v_fmac_f32_e32 v175, v92, v92
	v_fmac_f32_e32 v176, v88, v88
	v_fmac_f32_e32 v177, v84, v84
	v_fmac_f32_e32 v174, v97, v97
	v_fmac_f32_e32 v175, v93, v93
	v_fmac_f32_e32 v176, v89, v89
	v_fmac_f32_e32 v177, v85, v85
	v_add_f32_e32 v174, v174, v175
	v_add_f32_e32 v176, v176, v177
	v_add_f32_e32 v178, v174, v176
	ds_bpermute_b32 v179, v131, v178
	v_permlane16_swap_b32_e32 v166, v168
	v_permlane16_swap_b32_e32 v167, v169
	v_permlane16_swap_b32_e32 v170, v172
	v_permlane16_swap_b32_e32 v171, v173
	v_add_u32_e32 v253, 0x10000, v252
	global_store_dwordx4 v253, v[166:169], s[14:15] nt
	global_store_dwordx4 v253, v[170:173], s[14:15] offset:256 nt
	s_waitcnt lgkmcnt(0)
	v_add_f32_e32 v178, v178, v179
	ds_bpermute_b32 v179, v135, v178
	s_waitcnt lgkmcnt(0)
	v_add_f32_e32 v178, v178, v179
	s_and_saveexec_b64 s[30:31], s[8:9]
	global_store_dword v189, v178, s[16:17] offset:2048
	s_or_b64 exec, exec, s[30:31]
	s_waitcnt vmcnt(14)
	v_permlane16_swap_b32_e32 v228, v230
	v_permlane16_swap_b32_e32 v229, v231
	v_permlane16_swap_b32_e32 v232, v234
	v_permlane16_swap_b32_e32 v233, v235
	v_lshlrev_b32_e32 v166, 16, v228
	v_and_b32_e32 v167, 0xffff0000, v228
	v_lshlrev_b32_e32 v168, 16, v229
	v_and_b32_e32 v169, 0xffff0000, v229
	v_lshlrev_b32_e32 v170, 16, v230
	v_and_b32_e32 v171, 0xffff0000, v230
	v_lshlrev_b32_e32 v172, 16, v231
	v_and_b32_e32 v173, 0xffff0000, v231
	v_lshlrev_b32_e32 v174, 16, v232
	v_and_b32_e32 v175, 0xffff0000, v232
	v_lshlrev_b32_e32 v176, 16, v233
	v_and_b32_e32 v177, 0xffff0000, v233
	v_lshlrev_b32_e32 v178, 16, v234
	v_and_b32_e32 v179, 0xffff0000, v234
	v_lshlrev_b32_e32 v180, 16, v235
	v_and_b32_e32 v181, 0xffff0000, v235
	v_pk_add_f32 v[78:79], v[78:79], v[166:167]
	v_pk_add_f32 v[80:81], v[80:81], v[168:169]
	v_pk_add_f32 v[74:75], v[74:75], v[170:171]
	v_pk_add_f32 v[76:77], v[76:77], v[172:173]
	v_pk_add_f32 v[70:71], v[70:71], v[174:175]
	v_pk_add_f32 v[72:73], v[72:73], v[176:177]
	v_pk_add_f32 v[66:67], v[66:67], v[178:179]
	v_pk_add_f32 v[68:69], v[68:69], v[180:181]
	v_cvt_pk_bf16_f32 v166, v78, v79
	v_cvt_pk_bf16_f32 v167, v80, v81
	v_cvt_pk_bf16_f32 v168, v74, v75
	v_cvt_pk_bf16_f32 v169, v76, v77
	v_cvt_pk_bf16_f32 v170, v70, v71
	v_cvt_pk_bf16_f32 v171, v72, v73
	v_cvt_pk_bf16_f32 v172, v66, v67
	v_cvt_pk_bf16_f32 v173, v68, v69
	v_mul_f32_e32 v174, v78, v78
	v_mul_f32_e32 v175, v74, v74
	v_mul_f32_e32 v176, v70, v70
	v_mul_f32_e32 v177, v66, v66
	v_fmac_f32_e32 v174, v79, v79
	v_fmac_f32_e32 v175, v75, v75
	v_fmac_f32_e32 v176, v71, v71
	v_fmac_f32_e32 v177, v67, v67
	v_fmac_f32_e32 v174, v80, v80
	v_fmac_f32_e32 v175, v76, v76
	v_fmac_f32_e32 v176, v72, v72
	v_fmac_f32_e32 v177, v68, v68
	v_fmac_f32_e32 v174, v81, v81
	v_fmac_f32_e32 v175, v77, v77
	v_fmac_f32_e32 v176, v73, v73
	v_fmac_f32_e32 v177, v69, v69
	v_add_f32_e32 v174, v174, v175
	v_add_f32_e32 v176, v176, v177
	v_add_f32_e32 v178, v174, v176
	ds_bpermute_b32 v179, v131, v178
	v_permlane16_swap_b32_e32 v166, v168
	v_permlane16_swap_b32_e32 v167, v169
	v_permlane16_swap_b32_e32 v170, v172
	v_permlane16_swap_b32_e32 v171, v173
	v_add_u32_e32 v253, 0x18000, v252
	global_store_dwordx4 v253, v[166:169], s[14:15] nt
	global_store_dwordx4 v253, v[170:173], s[14:15] offset:256 nt
	s_waitcnt lgkmcnt(0)
	v_add_f32_e32 v178, v178, v179
	ds_bpermute_b32 v179, v135, v178
	s_waitcnt lgkmcnt(0)
	v_add_f32_e32 v178, v178, v179
	s_and_saveexec_b64 s[30:31], s[8:9]
	global_store_dword v189, v178, s[16:17] offset:3072
	s_or_b64 exec, exec, s[30:31]
	s_waitcnt vmcnt(14)
; __device__ __forceinline__ float bf_lo(unsigned u) { return __uint_as_float(u << 16); }
; __device__ __forceinline__ float bf_hi(unsigned u) { return __uint_as_float(u & 0xffff0000u); }
; __device__ __forceinline__ unsigned pk_bf16(float lo, float hi) { const f32x2 v = {lo, hi}; const bf16x2_t b = __builtin_convertvector(v, bf16x2_t); return __builtin_bit_cast(unsigned, b); }
;     __device__ __forceinline__ void operator()(const f32x4 (&acc)[2][2][4][2], const pg8::Unit& u, int wr, int wc, int fr, int fq) const {
;     ...
;                 const int row = row0 + ai * 128 + m * 16; const size_t off = (size_t)row * DM + col0; float q = 0.f;
;                 f32x4 r4[2][2];
;                 if (rf32) {
; #pragma unroll
;                     for (int bj = 0; bj < 2; ++bj)
; #pragma unroll
;                         for (int n = 0; n < 2; ++n) r4[bj][n] = *(const f32x4*)(rp + off + bj * 128 + n * 16);
;                 } else {
; #pragma unroll
;                     for (int bj = 0; bj < 2; ++bj)
; #pragma unroll
;                         for (int n = 0; n < 2; ++n) { const u32x2 w = *(const u32x2*)(XB + off + bj * 128 + n * 16); r4[bj][n] = (f32x4){bf_lo(w.x), bf_hi(w.x), bf_lo(w.y), bf_hi(w.y)}; }
;                 }
; #pragma unroll
;                 for (int bj = 0; bj < 2; ++bj)
; #pragma unroll
;                     for (int n = 0; n < 2; ++n) { const f32x4 x4 = r4[bj][n] + acc[ai][bj][m][n];
;                         q += (x4[0] * x4[0] + x4[1] * x4[1]) + (x4[2] * x4[2] + x4[3] * x4[3]);
;                         u32x2 w; w.x = pk_bf16(x4[0], x4[1]); w.y = pk_bf16(x4[2], x4[3]); *(u32x2*)(XB + off + bj * 128 + n * 16) = w; }
;                 q += __shfl_xor(q, 16); q += __shfl_xor(q, 32);
;                 if (fq == 0) ssq[(size_t)row * 16 + u.pn * 4 + wc] = q;
;                 if (m & 1) asm volatile("" ::: "memory");
;             }
	v_permlane16_swap_b32_e32 v236, v238
	v_permlane16_swap_b32_e32 v237, v239
	v_permlane16_swap_b32_e32 v240, v242
	v_permlane16_swap_b32_e32 v241, v243
	v_lshlrev_b32_e32 v166, 16, v236
	v_and_b32_e32 v167, 0xffff0000, v236
	v_lshlrev_b32_e32 v168, 16, v237
	v_and_b32_e32 v169, 0xffff0000, v237
	v_lshlrev_b32_e32 v170, 16, v238
	v_and_b32_e32 v171, 0xffff0000, v238
	v_lshlrev_b32_e32 v172, 16, v239
	v_and_b32_e32 v173, 0xffff0000, v239
	v_lshlrev_b32_e32 v174, 16, v240
	v_and_b32_e32 v175, 0xffff0000, v240
	v_lshlrev_b32_e32 v176, 16, v241
	v_and_b32_e32 v177, 0xffff0000, v241
	v_lshlrev_b32_e32 v178, 16, v242
	v_and_b32_e32 v179, 0xffff0000, v242
	v_lshlrev_b32_e32 v180, 16, v243
	v_and_b32_e32 v181, 0xffff0000, v243
	v_pk_add_f32 v[62:63], v[62:63], v[166:167]
	v_pk_add_f32 v[64:65], v[64:65], v[168:169]
	v_pk_add_f32 v[58:59], v[58:59], v[170:171]
	v_pk_add_f32 v[60:61], v[60:61], v[172:173]
	v_pk_add_f32 v[54:55], v[54:55], v[174:175]
	v_pk_add_f32 v[56:57], v[56:57], v[176:177]
	v_pk_add_f32 v[50:51], v[50:51], v[178:179]
	v_pk_add_f32 v[52:53], v[52:53], v[180:181]
	v_cvt_pk_bf16_f32 v166, v62, v63
	v_cvt_pk_bf16_f32 v167, v64, v65
	v_cvt_pk_bf16_f32 v168, v58, v59
	v_cvt_pk_bf16_f32 v169, v60, v61
	v_cvt_pk_bf16_f32 v170, v54, v55
	v_cvt_pk_bf16_f32 v171, v56, v57
	v_cvt_pk_bf16_f32 v172, v50, v51
	v_cvt_pk_bf16_f32 v173, v52, v53
	v_mul_f32_e32 v174, v62, v62
	v_mul_f32_e32 v175, v58, v58
	v_mul_f32_e32 v176, v54, v54
	v_mul_f32_e32 v177, v50, v50
	v_fmac_f32_e32 v174, v63, v63
	v_fmac_f32_e32 v175, v59, v59
	v_fmac_f32_e32 v176, v55, v55
	v_fmac_f32_e32 v177, v51, v51
	v_fmac_f32_e32 v174, v64, v64
	v_fmac_f32_e32 v175, v60, v60
	v_fmac_f32_e32 v176, v56, v56
	v_fmac_f32_e32 v177, v52, v52
	v_fmac_f32_e32 v174, v65, v65
	v_fmac_f32_e32 v175, v61, v61
	v_fmac_f32_e32 v176, v57, v57
	v_fmac_f32_e32 v177, v53, v53
	v_add_f32_e32 v174, v174, v175
	v_add_f32_e32 v176, v176, v177
	v_add_f32_e32 v178, v174, v176
	ds_bpermute_b32 v179, v131, v178
	v_permlane16_swap_b32_e32 v166, v168
	v_permlane16_swap_b32_e32 v167, v169
	v_permlane16_swap_b32_e32 v170, v172
	v_permlane16_swap_b32_e32 v171, v173
	v_add_u32_e32 v253, 0x40000, v252
	global_store_dwordx4 v253, v[166:169], s[14:15] nt
	global_store_dwordx4 v253, v[170:173], s[14:15] offset:256 nt
	s_waitcnt lgkmcnt(0)
	v_add_f32_e32 v178, v178, v179
	ds_bpermute_b32 v179, v135, v178
	v_add_u32_e32 v189, 0x2000, v189
	s_waitcnt lgkmcnt(0)
	v_add_f32_e32 v178, v178, v179
	s_and_saveexec_b64 s[30:31], s[8:9]
	global_store_dword v189, v178, s[16:17]
	s_or_b64 exec, exec, s[30:31]
	s_waitcnt vmcnt(14)
	v_permlane16_swap_b32_e32 v244, v246
	v_permlane16_swap_b32_e32 v245, v247
	v_permlane16_swap_b32_e32 v248, v250
	v_permlane16_swap_b32_e32 v249, v251
	v_lshlrev_b32_e32 v166, 16, v244
	v_and_b32_e32 v167, 0xffff0000, v244
	v_lshlrev_b32_e32 v168, 16, v245
	v_and_b32_e32 v169, 0xffff0000, v245
	v_lshlrev_b32_e32 v170, 16, v246
	v_and_b32_e32 v171, 0xffff0000, v246
	v_lshlrev_b32_e32 v172, 16, v247
	v_and_b32_e32 v173, 0xffff0000, v247
	v_lshlrev_b32_e32 v174, 16, v248
	v_and_b32_e32 v175, 0xffff0000, v248
	v_lshlrev_b32_e32 v176, 16, v249
	v_and_b32_e32 v177, 0xffff0000, v249
	v_lshlrev_b32_e32 v178, 16, v250
	v_and_b32_e32 v179, 0xffff0000, v250
	v_lshlrev_b32_e32 v180, 16, v251
	v_and_b32_e32 v181, 0xffff0000, v251
	v_pk_add_f32 v[46:47], v[46:47], v[166:167]
	v_pk_add_f32 v[48:49], v[48:49], v[168:169]
	v_pk_add_f32 v[42:43], v[42:43], v[170:171]
	v_pk_add_f32 v[44:45], v[44:45], v[172:173]
	v_pk_add_f32 v[38:39], v[38:39], v[174:175]
	v_pk_add_f32 v[40:41], v[40:41], v[176:177]
	v_pk_add_f32 v[34:35], v[34:35], v[178:179]
	v_pk_add_f32 v[36:37], v[36:37], v[180:181]
	v_cvt_pk_bf16_f32 v166, v46, v47
	v_cvt_pk_bf16_f32 v167, v48, v49
	v_cvt_pk_bf16_f32 v168, v42, v43
	v_cvt_pk_bf16_f32 v169, v44, v45
	v_cvt_pk_bf16_f32 v170, v38, v39
	v_cvt_pk_bf16_f32 v171, v40, v41
	v_cvt_pk_bf16_f32 v172, v34, v35
	v_cvt_pk_bf16_f32 v173, v36, v37
	v_mul_f32_e32 v174, v46, v46
	v_mul_f32_e32 v175, v42, v42
	v_mul_f32_e32 v176, v38, v38
	v_mul_f32_e32 v177, v34, v34
	v_fmac_f32_e32 v174, v47, v47
	v_fmac_f32_e32 v175, v43, v43
	v_fmac_f32_e32 v176, v39, v39
	v_fmac_f32_e32 v177, v35, v35
	v_fmac_f32_e32 v174, v48, v48
	v_fmac_f32_e32 v175, v44, v44
	v_fmac_f32_e32 v176, v40, v40
	v_fmac_f32_e32 v177, v36, v36
	v_fmac_f32_e32 v174, v49, v49
	v_fmac_f32_e32 v175, v45, v45
	v_fmac_f32_e32 v176, v41, v41
	v_fmac_f32_e32 v177, v37, v37
	v_add_f32_e32 v174, v174, v175
	v_add_f32_e32 v176, v176, v177
	v_add_f32_e32 v178, v174, v176
	ds_bpermute_b32 v179, v131, v178
	v_permlane16_swap_b32_e32 v166, v168
	v_permlane16_swap_b32_e32 v167, v169
	v_permlane16_swap_b32_e32 v170, v172
	v_permlane16_swap_b32_e32 v171, v173
	v_add_u32_e32 v253, 0x48000, v252
	global_store_dwordx4 v253, v[166:169], s[14:15] nt
	global_store_dwordx4 v253, v[170:173], s[14:15] offset:256 nt
	s_waitcnt lgkmcnt(0)
	v_add_f32_e32 v178, v178, v179
	ds_bpermute_b32 v179, v135, v178
	s_waitcnt lgkmcnt(0)
	v_add_f32_e32 v178, v178, v179
	s_and_saveexec_b64 s[30:31], s[8:9]
	global_store_dword v189, v178, s[16:17] offset:1024
	s_or_b64 exec, exec, s[30:31]
	s_waitcnt vmcnt(14)
; __device__ __forceinline__ float bf_lo(unsigned u) { return __uint_as_float(u << 16); }
; __device__ __forceinline__ float bf_hi(unsigned u) { return __uint_as_float(u & 0xffff0000u); }
; __device__ __forceinline__ unsigned pk_bf16(float lo, float hi) { const f32x2 v = {lo, hi}; const bf16x2_t b = __builtin_convertvector(v, bf16x2_t); return __builtin_bit_cast(unsigned, b); }
;     __device__ __forceinline__ void operator()(const f32x4 (&acc)[2][2][4][2], const pg8::Unit& u, int wr, int wc, int fr, int fq) const {
;     ...
;                 const int row = row0 + ai * 128 + m * 16; const size_t off = (size_t)row * DM + col0; float q = 0.f;
;                 f32x4 r4[2][2];
;                 if (rf32) {
; #pragma unroll
;                     for (int bj = 0; bj < 2; ++bj)
; #pragma unroll
;                         for (int n = 0; n < 2; ++n) r4[bj][n] = *(const f32x4*)(rp + off + bj * 128 + n * 16);
;                 } else {
; #pragma unroll
;                     for (int bj = 0; bj < 2; ++bj)
; #pragma unroll
;                         for (int n = 0; n < 2; ++n) { const u32x2 w = *(const u32x2*)(XB + off + bj * 128 + n * 16); r4[bj][n] = (f32x4){bf_lo(w.x), bf_hi(w.x), bf_lo(w.y), bf_hi(w.y)}; }
;                 }
; #pragma unroll
;                 for (int bj = 0; bj < 2; ++bj)
; #pragma unroll
;                     for (int n = 0; n < 2; ++n) { const f32x4 x4 = r4[bj][n] + acc[ai][bj][m][n];
;                         q += (x4[0] * x4[0] + x4[1] * x4[1]) + (x4[2] * x4[2] + x4[3] * x4[3]);
;                         u32x2 w; w.x = pk_bf16(x4[0], x4[1]); w.y = pk_bf16(x4[2], x4[3]); *(u32x2*)(XB + off + bj * 128 + n * 16) = w; }
;                 q += __shfl_xor(q, 16); q += __shfl_xor(q, 32);
;                 if (fq == 0) ssq[(size_t)row * 16 + u.pn * 4 + wc] = q;
;                 if (m & 1) asm volatile("" ::: "memory");
;             }
	v_permlane16_swap_b32_e32 v204, v206
	v_permlane16_swap_b32_e32 v205, v207
	v_permlane16_swap_b32_e32 v208, v210
	v_permlane16_swap_b32_e32 v209, v211
	v_lshlrev_b32_e32 v166, 16, v204
	v_and_b32_e32 v167, 0xffff0000, v204
	v_lshlrev_b32_e32 v168, 16, v205
	v_and_b32_e32 v169, 0xffff0000, v205
	v_lshlrev_b32_e32 v170, 16, v206
	v_and_b32_e32 v171, 0xffff0000, v206
	v_lshlrev_b32_e32 v172, 16, v207
	v_and_b32_e32 v173, 0xffff0000, v207
	v_lshlrev_b32_e32 v174, 16, v208
	v_and_b32_e32 v175, 0xffff0000, v208
	v_lshlrev_b32_e32 v176, 16, v209
	v_and_b32_e32 v177, 0xffff0000, v209
	v_lshlrev_b32_e32 v178, 16, v210
	v_and_b32_e32 v179, 0xffff0000, v210
	v_lshlrev_b32_e32 v180, 16, v211
	v_and_b32_e32 v181, 0xffff0000, v211
	v_pk_add_f32 v[30:31], v[30:31], v[166:167]
	v_pk_add_f32 v[32:33], v[32:33], v[168:169]
	v_pk_add_f32 v[26:27], v[26:27], v[170:171]
	v_pk_add_f32 v[28:29], v[28:29], v[172:173]
	v_pk_add_f32 v[22:23], v[22:23], v[174:175]
	v_pk_add_f32 v[24:25], v[24:25], v[176:177]
	v_pk_add_f32 v[18:19], v[18:19], v[178:179]
	v_pk_add_f32 v[20:21], v[20:21], v[180:181]
	v_cvt_pk_bf16_f32 v166, v30, v31
	v_cvt_pk_bf16_f32 v167, v32, v33
	v_cvt_pk_bf16_f32 v168, v26, v27
	v_cvt_pk_bf16_f32 v169, v28, v29
	v_cvt_pk_bf16_f32 v170, v22, v23
	v_cvt_pk_bf16_f32 v171, v24, v25
	v_cvt_pk_bf16_f32 v172, v18, v19
	v_cvt_pk_bf16_f32 v173, v20, v21
	v_mul_f32_e32 v174, v30, v30
	v_mul_f32_e32 v175, v26, v26
	v_mul_f32_e32 v176, v22, v22
	v_mul_f32_e32 v177, v18, v18
	v_fmac_f32_e32 v174, v31, v31
	v_fmac_f32_e32 v175, v27, v27
	v_fmac_f32_e32 v176, v23, v23
	v_fmac_f32_e32 v177, v19, v19
	v_fmac_f32_e32 v174, v32, v32
	v_fmac_f32_e32 v175, v28, v28
	v_fmac_f32_e32 v176, v24, v24
	v_fmac_f32_e32 v177, v20, v20
	v_fmac_f32_e32 v174, v33, v33
	v_fmac_f32_e32 v175, v29, v29
	v_fmac_f32_e32 v176, v25, v25
	v_fmac_f32_e32 v177, v21, v21
	v_add_f32_e32 v174, v174, v175
	v_add_f32_e32 v176, v176, v177
	v_add_f32_e32 v178, v174, v176
	ds_bpermute_b32 v179, v131, v178
	v_permlane16_swap_b32_e32 v166, v168
	v_permlane16_swap_b32_e32 v167, v169
	v_permlane16_swap_b32_e32 v170, v172
	v_permlane16_swap_b32_e32 v171, v173
	v_add_u32_e32 v253, 0x50000, v252
	global_store_dwordx4 v253, v[166:169], s[14:15] nt
	global_store_dwordx4 v253, v[170:173], s[14:15] offset:256 nt
	s_waitcnt lgkmcnt(0)
	v_add_f32_e32 v178, v178, v179
	ds_bpermute_b32 v179, v135, v178
	s_waitcnt lgkmcnt(0)
	v_add_f32_e32 v178, v178, v179
	s_and_saveexec_b64 s[30:31], s[8:9]
	global_store_dword v189, v178, s[16:17] offset:2048
	s_or_b64 exec, exec, s[30:31]
	s_waitcnt vmcnt(12)
	v_permlane16_swap_b32_e32 v212, v214
	v_permlane16_swap_b32_e32 v213, v215
	v_permlane16_swap_b32_e32 v216, v218
	v_permlane16_swap_b32_e32 v217, v219
	v_lshlrev_b32_e32 v166, 16, v212
	v_and_b32_e32 v167, 0xffff0000, v212
	v_lshlrev_b32_e32 v168, 16, v213
	v_and_b32_e32 v169, 0xffff0000, v213
	v_lshlrev_b32_e32 v170, 16, v214
	v_and_b32_e32 v171, 0xffff0000, v214
	v_lshlrev_b32_e32 v172, 16, v215
	v_and_b32_e32 v173, 0xffff0000, v215
	v_lshlrev_b32_e32 v174, 16, v216
	v_and_b32_e32 v175, 0xffff0000, v216
	v_lshlrev_b32_e32 v176, 16, v217
	v_and_b32_e32 v177, 0xffff0000, v217
	v_lshlrev_b32_e32 v178, 16, v218
	v_and_b32_e32 v179, 0xffff0000, v218
	v_lshlrev_b32_e32 v180, 16, v219
	v_and_b32_e32 v181, 0xffff0000, v219
	v_pk_add_f32 v[14:15], v[14:15], v[166:167]
	v_pk_add_f32 v[16:17], v[16:17], v[168:169]
	v_pk_add_f32 v[10:11], v[10:11], v[170:171]
	v_pk_add_f32 v[12:13], v[12:13], v[172:173]
	v_pk_add_f32 v[6:7], v[6:7], v[174:175]
	v_pk_add_f32 v[8:9], v[8:9], v[176:177]
	v_pk_add_f32 v[2:3], v[2:3], v[178:179]
	v_pk_add_f32 v[4:5], v[4:5], v[180:181]
	v_cvt_pk_bf16_f32 v166, v14, v15
	v_cvt_pk_bf16_f32 v167, v16, v17
	v_cvt_pk_bf16_f32 v168, v10, v11
	v_cvt_pk_bf16_f32 v169, v12, v13
	v_cvt_pk_bf16_f32 v170, v6, v7
	v_cvt_pk_bf16_f32 v171, v8, v9
	v_cvt_pk_bf16_f32 v172, v2, v3
	v_cvt_pk_bf16_f32 v173, v4, v5
	v_mul_f32_e32 v174, v14, v14
	v_mul_f32_e32 v175, v10, v10
	v_mul_f32_e32 v176, v6, v6
	v_mul_f32_e32 v177, v2, v2
	v_fmac_f32_e32 v174, v15, v15
	v_fmac_f32_e32 v175, v11, v11
	v_fmac_f32_e32 v176, v7, v7
	v_fmac_f32_e32 v177, v3, v3
	v_fmac_f32_e32 v174, v16, v16
	v_fmac_f32_e32 v175, v12, v12
	v_fmac_f32_e32 v176, v8, v8
	v_fmac_f32_e32 v177, v4, v4
	v_fmac_f32_e32 v174, v17, v17
	v_fmac_f32_e32 v175, v13, v13
	v_fmac_f32_e32 v176, v9, v9
	v_fmac_f32_e32 v177, v5, v5
	v_add_f32_e32 v174, v174, v175
	v_add_f32_e32 v176, v176, v177
	v_add_f32_e32 v178, v174, v176
	ds_bpermute_b32 v179, v131, v178
	v_permlane16_swap_b32_e32 v166, v168
	v_permlane16_swap_b32_e32 v167, v169
	v_permlane16_swap_b32_e32 v170, v172
	v_permlane16_swap_b32_e32 v171, v173
	v_add_u32_e32 v253, 0x58000, v252
	global_store_dwordx4 v253, v[166:169], s[14:15] nt
	global_store_dwordx4 v253, v[170:173], s[14:15] offset:256 nt
	s_waitcnt lgkmcnt(0)
	v_add_f32_e32 v178, v178, v179
	ds_bpermute_b32 v179, v135, v178
	s_waitcnt lgkmcnt(0)
	v_add_f32_e32 v178, v178, v179
	s_and_saveexec_b64 s[30:31], s[8:9]
	global_store_dword v189, v178, s[16:17] offset:3072
	s_or_b64 exec, exec, s[30:31]

; __device__ __forceinline__ float bf_lo(unsigned u) { return __uint_as_float(u << 16); }
; __device__ __forceinline__ float bf_hi(unsigned u) { return __uint_as_float(u & 0xffff0000u); }
; __device__ __forceinline__ unsigned pk_bf16(float lo, float hi) { const f32x2 v = {lo, hi}; const bf16x2_t b = __builtin_convertvector(v, bf16x2_t); return __builtin_bit_cast(unsigned, b); }
;     __device__ __forceinline__ void operator()(const f32x4 (&acc)[2][2][4][2], const pg8::Unit& u, int wr, int wc, int fr, int fq) const {
;         asm volatile("" : "+v"(fr));
;         const int row0 = u.pm * 256 + wr * 64 + fr, col0 = u.pn * 256 + wc * 32 + 4 * fq;
;         const bool rf32 = (rp != nullptr) && (u.pm < MP / 256);
; #pragma unroll
;         for (int ai = 0; ai < 2; ++ai)
; #pragma unroll
;             for (int m = 0; m < 4; ++m) {
;                 const int row = row0 + ai * 128 + m * 16; const size_t off = (size_t)row * DM + col0; float q = 0.f;
;                 f32x4 r4[2][2];
;                 if (rf32) {
; #pragma unroll
;                     for (int bj = 0; bj < 2; ++bj)
; #pragma unroll
;                         for (int n = 0; n < 2; ++n) r4[bj][n] = *(const f32x4*)(rp + off + bj * 128 + n * 16);
;                 } else {
; #pragma unroll
;                     for (int bj = 0; bj < 2; ++bj)
; #pragma unroll
;                         for (int n = 0; n < 2; ++n) { const u32x2 w = *(const u32x2*)(XB + off + bj * 128 + n * 16); r4[bj][n] = (f32x4){bf_lo(w.x), bf_hi(w.x), bf_lo(w.y), bf_hi(w.y)}; }
;                 }
; #pragma unroll
;                 for (int bj = 0; bj < 2; ++bj)
; #pragma unroll
;                     for (int n = 0; n < 2; ++n) { const f32x4 x4 = r4[bj][n] + acc[ai][bj][m][n];
;                         q += (x4[0] * x4[0] + x4[1] * x4[1]) + (x4[2] * x4[2] + x4[3] * x4[3]);
;                         u32x2 w; w.x = pk_bf16(x4[0], x4[1]); w.y = pk_bf16(x4[2], x4[3]); *(u32x2*)(XB + off + bj * 128 + n * 16) = w; }
;                 q += __shfl_xor(q, 16); q += __shfl_xor(q, 32);
;                 if (fq == 0) ssq[(size_t)row * 16 + u.pn * 4 + wc] = q;
;                 if (m & 1) asm volatile("" ::: "memory");
;             }
.LBB0_1893:
	s_lshl_b32 s4, s47, 8
	v_mov_b32_e32 v158, v1
	s_add_i32 s4, s4, s40
	s_lshl_b32 s22, s46, 2
	v_add_u32_e32 v160, s4, v158
	v_ashrrev_i32_e32 v161, 31, v160
	v_lshl_or_b32 v158, s46, 8, v163
	v_lshlrev_b64 v[166:167], 11, v[160:161]
	v_ashrrev_i32_e32 v159, 31, v158
	v_lshl_add_u64 v[166:167], s[14:15], 0, v[166:167]
	v_lshl_add_u64 v[166:167], v[158:159], 1, v[166:167]
	s_ashr_i32 s23, s22, 31
	v_lshlrev_b32_e32 v252, 11, v160
	v_lshl_add_u32 v252, v158, 1, v252
	v_bfe_u32 v253, v190, 4, 1
	v_mul_u32_u24_e32 v253, 24, v253
	v_add_u32_e32 v252, v252, v253
	s_lshl_b32 s88, s39, 2
	v_lshl_add_u32 v189, v160, 6, s88
	v_lshl_add_u32 v189, s22, 2, v189
	global_load_dwordx4 v[204:207], v252, s[14:15]
	global_load_dwordx4 v[208:211], v252, s[14:15] offset:256
	v_add_u32_e32 v253, 0x8000, v252
	global_load_dwordx4 v[212:215], v253, s[14:15]
	global_load_dwordx4 v[216:219], v253, s[14:15] offset:256
	v_add_u32_e32 v253, 0x10000, v252
	global_load_dwordx4 v[220:223], v253, s[14:15]
	global_load_dwordx4 v[224:227], v253, s[14:15] offset:256
	v_add_u32_e32 v253, 0x18000, v252
	global_load_dwordx4 v[228:231], v253, s[14:15]
	global_load_dwordx4 v[232:235], v253, s[14:15] offset:256
	v_add_u32_e32 v253, 0x40000, v252
	global_load_dwordx4 v[236:239], v253, s[14:15]
	global_load_dwordx4 v[240:243], v253, s[14:15] offset:256
	v_add_u32_e32 v253, 0x48000, v252
	global_load_dwordx4 v[244:247], v253, s[14:15]
	global_load_dwordx4 v[248:251], v253, s[14:15] offset:256
	s_waitcnt vmcnt(10)
	v_permlane16_swap_b32_e32 v204, v206
	v_permlane16_swap_b32_e32 v205, v207
	v_permlane16_swap_b32_e32 v208, v210
	v_permlane16_swap_b32_e32 v209, v211
	v_lshlrev_b32_e32 v166, 16, v204
	v_and_b32_e32 v167, 0xffff0000, v204
	v_lshlrev_b32_e32 v168, 16, v205
	v_and_b32_e32 v169, 0xffff0000, v205
	v_lshlrev_b32_e32 v170, 16, v206
	v_and_b32_e32 v171, 0xffff0000, v206
	v_lshlrev_b32_e32 v172, 16, v207
	v_and_b32_e32 v173, 0xffff0000, v207
	v_lshlrev_b32_e32 v174, 16, v208
	v_and_b32_e32 v175, 0xffff0000, v208
	v_lshlrev_b32_e32 v176, 16, v209
	v_and_b32_e32 v177, 0xffff0000, v209
	v_lshlrev_b32_e32 v178, 16, v210
	v_and_b32_e32 v179, 0xffff0000, v210
	v_lshlrev_b32_e32 v180, 16, v211
	v_and_b32_e32 v181, 0xffff0000, v211
	v_pk_add_f32 v[126:127], v[126:127], v[166:167]
	v_pk_add_f32 v[128:129], v[128:129], v[168:169]
	v_pk_add_f32 v[122:123], v[122:123], v[170:171]
	v_pk_add_f32 v[124:125], v[124:125], v[172:173]
	v_pk_add_f32 v[118:119], v[118:119], v[174:175]
	v_pk_add_f32 v[120:121], v[120:121], v[176:177]
	v_pk_add_f32 v[114:115], v[114:115], v[178:179]
	v_pk_add_f32 v[116:117], v[116:117], v[180:181]
	v_add_u32_e32 v253, 0x50000, v252
	global_load_dwordx4 v[204:207], v253, s[14:15]
	global_load_dwordx4 v[208:211], v253, s[14:15] offset:256
	v_cvt_pk_bf16_f32 v166, v126, v127
	v_cvt_pk_bf16_f32 v167, v128, v129
	v_cvt_pk_bf16_f32 v168, v122, v123
	v_cvt_pk_bf16_f32 v169, v124, v125
	v_cvt_pk_bf16_f32 v170, v118, v119
	v_cvt_pk_bf16_f32 v171, v120, v121
	v_cvt_pk_bf16_f32 v172, v114, v115
	v_cvt_pk_bf16_f32 v173, v116, v117
	v_mul_f32_e32 v174, v126, v126
	v_mul_f32_e32 v175, v122, v122
	v_mul_f32_e32 v176, v118, v118
	v_mul_f32_e32 v177, v114, v114
	v_fmac_f32_e32 v174, v127, v127
	v_fmac_f32_e32 v175, v123, v123
	v_fmac_f32_e32 v176, v119, v119
	v_fmac_f32_e32 v177, v115, v115
	v_fmac_f32_e32 v174, v128, v128
	v_fmac_f32_e32 v175, v124, v124
	v_fmac_f32_e32 v176, v120, v120
	v_fmac_f32_e32 v177, v116, v116
	v_fmac_f32_e32 v174, v129, v129
	v_fmac_f32_e32 v175, v125, v125
	v_fmac_f32_e32 v176, v121, v121
	v_fmac_f32_e32 v177, v117, v117
	v_add_f32_e32 v174, v174, v175
	v_add_f32_e32 v176, v176, v177
	v_add_f32_e32 v178, v174, v176
	ds_bpermute_b32 v179, v131, v178
	v_permlane16_swap_b32_e32 v166, v168
	v_permlane16_swap_b32_e32 v167, v169
	v_permlane16_swap_b32_e32 v170, v172
	v_permlane16_swap_b32_e32 v171, v173
	global_store_dwordx4 v252, v[166:169], s[14:15] nt
	global_store_dwordx4 v252, v[170:173], s[14:15] offset:256 nt
	s_waitcnt lgkmcnt(0)
	v_add_f32_e32 v178, v178, v179
	ds_bpermute_b32 v179, v135, v178
	s_waitcnt lgkmcnt(0)
	v_add_f32_e32 v178, v178, v179
	s_and_saveexec_b64 s[24:25], s[6:7]
	global_store_dword v189, v178, s[16:17]
	s_or_b64 exec, exec, s[24:25]
	s_waitcnt vmcnt(12)
	v_permlane16_swap_b32_e32 v212, v214
	v_permlane16_swap_b32_e32 v213, v215
	v_permlane16_swap_b32_e32 v216, v218
	v_permlane16_swap_b32_e32 v217, v219
	v_lshlrev_b32_e32 v166, 16, v212
	v_and_b32_e32 v167, 0xffff0000, v212
	v_lshlrev_b32_e32 v168, 16, v213
	v_and_b32_e32 v169, 0xffff0000, v213
	v_lshlrev_b32_e32 v170, 16, v214
	v_and_b32_e32 v171, 0xffff0000, v214
	v_lshlrev_b32_e32 v172, 16, v215
	v_and_b32_e32 v173, 0xffff0000, v215
	v_lshlrev_b32_e32 v174, 16, v216
	v_and_b32_e32 v175, 0xffff0000, v216
	v_lshlrev_b32_e32 v176, 16, v217
	v_and_b32_e32 v177, 0xffff0000, v217
	v_lshlrev_b32_e32 v178, 16, v218
	v_and_b32_e32 v179, 0xffff0000, v218
	v_lshlrev_b32_e32 v180, 16, v219
	v_and_b32_e32 v181, 0xffff0000, v219
	v_pk_add_f32 v[110:111], v[110:111], v[166:167]
	v_pk_add_f32 v[112:113], v[112:113], v[168:169]
	v_pk_add_f32 v[106:107], v[106:107], v[170:171]
	v_pk_add_f32 v[108:109], v[108:109], v[172:173]
	v_pk_add_f32 v[102:103], v[102:103], v[174:175]
	v_pk_add_f32 v[104:105], v[104:105], v[176:177]
	v_pk_add_f32 v[98:99], v[98:99], v[178:179]
	v_pk_add_f32 v[100:101], v[100:101], v[180:181]
	v_add_u32_e32 v253, 0x58000, v252
	global_load_dwordx4 v[212:215], v253, s[14:15]
	global_load_dwordx4 v[216:219], v253, s[14:15] offset:256
	v_cvt_pk_bf16_f32 v166, v110, v111
	v_cvt_pk_bf16_f32 v167, v112, v113
	v_cvt_pk_bf16_f32 v168, v106, v107
	v_cvt_pk_bf16_f32 v169, v108, v109
	v_cvt_pk_bf16_f32 v170, v102, v103
	v_cvt_pk_bf16_f32 v171, v104, v105
	v_cvt_pk_bf16_f32 v172, v98, v99
	v_cvt_pk_bf16_f32 v173, v100, v101
	v_mul_f32_e32 v174, v110, v110
	v_mul_f32_e32 v175, v106, v106
	v_mul_f32_e32 v176, v102, v102
	v_mul_f32_e32 v177, v98, v98
	v_fmac_f32_e32 v174, v111, v111
	v_fmac_f32_e32 v175, v107, v107
	v_fmac_f32_e32 v176, v103, v103
	v_fmac_f32_e32 v177, v99, v99
	v_fmac_f32_e32 v174, v112, v112
	v_fmac_f32_e32 v175, v108, v108
	v_fmac_f32_e32 v176, v104, v104
	v_fmac_f32_e32 v177, v100, v100
	v_fmac_f32_e32 v174, v113, v113
	v_fmac_f32_e32 v175, v109, v109
	v_fmac_f32_e32 v176, v105, v105
	v_fmac_f32_e32 v177, v101, v101
	v_add_f32_e32 v174, v174, v175
	v_add_f32_e32 v176, v176, v177
	v_add_f32_e32 v178, v174, v176
	ds_bpermute_b32 v179, v131, v178
	v_permlane16_swap_b32_e32 v166, v168
	v_permlane16_swap_b32_e32 v167, v169
	v_permlane16_swap_b32_e32 v170, v172
	v_permlane16_swap_b32_e32 v171, v173
	v_add_u32_e32 v253, 0x8000, v252
	global_store_dwordx4 v253, v[166:169], s[14:15] nt
	global_store_dwordx4 v253, v[170:173], s[14:15] offset:256 nt
	s_waitcnt lgkmcnt(0)
; __device__ __forceinline__ float bf_lo(unsigned u) { return __uint_as_float(u << 16); }
; __device__ __forceinline__ float bf_hi(unsigned u) { return __uint_as_float(u & 0xffff0000u); }
; __device__ __forceinline__ unsigned pk_bf16(float lo, float hi) { const f32x2 v = {lo, hi}; const bf16x2_t b = __builtin_convertvector(v, bf16x2_t); return __builtin_bit_cast(unsigned, b); }
;     __device__ __forceinline__ void operator()(const f32x4 (&acc)[2][2][4][2], const pg8::Unit& u, int wr, int wc, int fr, int fq) const {
;     ...
;                     for (int bj = 0; bj < 2; ++bj)
; #pragma unroll
;                         for (int n = 0; n < 2; ++n) { const u32x2 w = *(const u32x2*)(XB + off + bj * 128 + n * 16); r4[bj][n] = (f32x4){bf_lo(w.x), bf_hi(w.x), bf_lo(w.y), bf_hi(w.y)}; }
;                 }
; #pragma unroll
;                 for (int bj = 0; bj < 2; ++bj)
; #pragma unroll
;                     for (int n = 0; n < 2; ++n) { const f32x4 x4 = r4[bj][n] + acc[ai][bj][m][n];
;                         q += (x4[0] * x4[0] + x4[1] * x4[1]) + (x4[2] * x4[2] + x4[3] * x4[3]);
;                         u32x2 w; w.x = pk_bf16(x4[0], x4[1]); w.y = pk_bf16(x4[2], x4[3]); *(u32x2*)(XB + off + bj * 128 + n * 16) = w; }
;                 q += __shfl_xor(q, 16); q += __shfl_xor(q, 32);
;                 if (fq == 0) ssq[(size_t)row * 16 + u.pn * 4 + wc] = q;
	v_add_f32_e32 v178, v178, v179
	ds_bpermute_b32 v179, v135, v178
	s_waitcnt lgkmcnt(0)
	v_add_f32_e32 v178, v178, v179
	s_and_saveexec_b64 s[24:25], s[6:7]
	global_store_dword v189, v178, s[16:17] offset:1024
	s_or_b64 exec, exec, s[24:25]
	s_waitcnt vmcnt(14)
	v_permlane16_swap_b32_e32 v220, v222
	v_permlane16_swap_b32_e32 v221, v223
	v_permlane16_swap_b32_e32 v224, v226
	v_permlane16_swap_b32_e32 v225, v227
	v_lshlrev_b32_e32 v166, 16, v220
	v_and_b32_e32 v167, 0xffff0000, v220
	v_lshlrev_b32_e32 v168, 16, v221
	v_and_b32_e32 v169, 0xffff0000, v221
	v_lshlrev_b32_e32 v170, 16, v222
	v_and_b32_e32 v171, 0xffff0000, v222
	v_lshlrev_b32_e32 v172, 16, v223
	v_and_b32_e32 v173, 0xffff0000, v223
	v_lshlrev_b32_e32 v174, 16, v224
	v_and_b32_e32 v175, 0xffff0000, v224
	v_lshlrev_b32_e32 v176, 16, v225
	v_and_b32_e32 v177, 0xffff0000, v225
	v_lshlrev_b32_e32 v178, 16, v226
	v_and_b32_e32 v179, 0xffff0000, v226
	v_lshlrev_b32_e32 v180, 16, v227
	v_and_b32_e32 v181, 0xffff0000, v227
	v_pk_add_f32 v[94:95], v[94:95], v[166:167]
	v_pk_add_f32 v[96:97], v[96:97], v[168:169]
	v_pk_add_f32 v[90:91], v[90:91], v[170:171]
	v_pk_add_f32 v[92:93], v[92:93], v[172:173]
	v_pk_add_f32 v[86:87], v[86:87], v[174:175]
	v_pk_add_f32 v[88:89], v[88:89], v[176:177]
	v_pk_add_f32 v[82:83], v[82:83], v[178:179]
	v_pk_add_f32 v[84:85], v[84:85], v[180:181]
	v_cvt_pk_bf16_f32 v166, v94, v95
	v_cvt_pk_bf16_f32 v167, v96, v97
	v_cvt_pk_bf16_f32 v168, v90, v91
	v_cvt_pk_bf16_f32 v169, v92, v93
	v_cvt_pk_bf16_f32 v170, v86, v87
	v_cvt_pk_bf16_f32 v171, v88, v89
	v_cvt_pk_bf16_f32 v172, v82, v83
	v_cvt_pk_bf16_f32 v173, v84, v85
	v_mul_f32_e32 v174, v94, v94
	v_mul_f32_e32 v175, v90, v90
	v_mul_f32_e32 v176, v86, v86
	v_mul_f32_e32 v177, v82, v82
	v_fmac_f32_e32 v174, v95, v95
	v_fmac_f32_e32 v175, v91, v91
	v_fmac_f32_e32 v176, v87, v87
	v_fmac_f32_e32 v177, v83, v83
	v_fmac_f32_e32 v174, v96, v96
	v_fmac_f32_e32 v175, v92, v92
	v_fmac_f32_e32 v176, v88, v88
	v_fmac_f32_e32 v177, v84, v84
	v_fmac_f32_e32 v174, v97, v97
	v_fmac_f32_e32 v175, v93, v93
	v_fmac_f32_e32 v176, v89, v89
	v_fmac_f32_e32 v177, v85, v85
	v_add_f32_e32 v174, v174, v175
	v_add_f32_e32 v176, v176, v177
	v_add_f32_e32 v178, v174, v176
	ds_bpermute_b32 v179, v131, v178
	v_permlane16_swap_b32_e32 v166, v168
	v_permlane16_swap_b32_e32 v167, v169
	v_permlane16_swap_b32_e32 v170, v172
	v_permlane16_swap_b32_e32 v171, v173
	v_add_u32_e32 v253, 0x10000, v252
	global_store_dwordx4 v253, v[166:169], s[14:15] nt
	global_store_dwordx4 v253, v[170:173], s[14:15] offset:256 nt
	s_waitcnt lgkmcnt(0)
	v_add_f32_e32 v178, v178, v179
	ds_bpermute_b32 v179, v135, v178
	s_waitcnt lgkmcnt(0)
	v_add_f32_e32 v178, v178, v179
	s_and_saveexec_b64 s[24:25], s[6:7]
	global_store_dword v189, v178, s[16:17] offset:2048
	s_or_b64 exec, exec, s[24:25]
	s_waitcnt vmcnt(14)
	v_permlane16_swap_b32_e32 v228, v230
	v_permlane16_swap_b32_e32 v229, v231
	v_permlane16_swap_b32_e32 v232, v234
	v_permlane16_swap_b32_e32 v233, v235
	v_lshlrev_b32_e32 v166, 16, v228
	v_and_b32_e32 v167, 0xffff0000, v228
	v_lshlrev_b32_e32 v168, 16, v229
	v_and_b32_e32 v169, 0xffff0000, v229
	v_lshlrev_b32_e32 v170, 16, v230
	v_and_b32_e32 v171, 0xffff0000, v230
	v_lshlrev_b32_e32 v172, 16, v231
	v_and_b32_e32 v173, 0xffff0000, v231
	v_lshlrev_b32_e32 v174, 16, v232
	v_and_b32_e32 v175, 0xffff0000, v232
	v_lshlrev_b32_e32 v176, 16, v233
	v_and_b32_e32 v177, 0xffff0000, v233
	v_lshlrev_b32_e32 v178, 16, v234
	v_and_b32_e32 v179, 0xffff0000, v234
	v_lshlrev_b32_e32 v180, 16, v235
	v_and_b32_e32 v181, 0xffff0000, v235
	v_pk_add_f32 v[78:79], v[78:79], v[166:167]
	v_pk_add_f32 v[80:81], v[80:81], v[168:169]
	v_pk_add_f32 v[74:75], v[74:75], v[170:171]
	v_pk_add_f32 v[76:77], v[76:77], v[172:173]
	v_pk_add_f32 v[70:71], v[70:71], v[174:175]
	v_pk_add_f32 v[72:73], v[72:73], v[176:177]
	v_pk_add_f32 v[66:67], v[66:67], v[178:179]
	v_pk_add_f32 v[68:69], v[68:69], v[180:181]
	v_cvt_pk_bf16_f32 v166, v78, v79
	v_cvt_pk_bf16_f32 v167, v80, v81
	v_cvt_pk_bf16_f32 v168, v74, v75
	v_cvt_pk_bf16_f32 v169, v76, v77
	v_cvt_pk_bf16_f32 v170, v70, v71
	v_cvt_pk_bf16_f32 v171, v72, v73
	v_cvt_pk_bf16_f32 v172, v66, v67
	v_cvt_pk_bf16_f32 v173, v68, v69
	v_mul_f32_e32 v174, v78, v78
	v_mul_f32_e32 v175, v74, v74
	v_mul_f32_e32 v176, v70, v70
	v_mul_f32_e32 v177, v66, v66
	v_fmac_f32_e32 v174, v79, v79
	v_fmac_f32_e32 v175, v75, v75
	v_fmac_f32_e32 v176, v71, v71
	v_fmac_f32_e32 v177, v67, v67
	v_fmac_f32_e32 v174, v80, v80
	v_fmac_f32_e32 v175, v76, v76
	v_fmac_f32_e32 v176, v72, v72
	v_fmac_f32_e32 v177, v68, v68
	v_fmac_f32_e32 v174, v81, v81
	v_fmac_f32_e32 v175, v77, v77
	v_fmac_f32_e32 v176, v73, v73
	v_fmac_f32_e32 v177, v69, v69
	v_add_f32_e32 v174, v174, v175
	v_add_f32_e32 v176, v176, v177
	v_add_f32_e32 v178, v174, v176
	ds_bpermute_b32 v179, v131, v178
	v_permlane16_swap_b32_e32 v166, v168
	v_permlane16_swap_b32_e32 v167, v169
	v_permlane16_swap_b32_e32 v170, v172
	v_permlane16_swap_b32_e32 v171, v173
	v_add_u32_e32 v253, 0x18000, v252
	global_store_dwordx4 v253, v[166:169], s[14:15] nt
	global_store_dwordx4 v253, v[170:173], s[14:15] offset:256 nt
	s_waitcnt lgkmcnt(0)
	v_add_f32_e32 v178, v178, v179
	ds_bpermute_b32 v179, v135, v178
	s_waitcnt lgkmcnt(0)
	v_add_f32_e32 v178, v178, v179
	s_and_saveexec_b64 s[24:25], s[6:7]
	global_store_dword v189, v178, s[16:17] offset:3072
	s_or_b64 exec, exec, s[24:25]
	s_waitcnt vmcnt(14)
; __device__ __forceinline__ float bf_lo(unsigned u) { return __uint_as_float(u << 16); }
; __device__ __forceinline__ float bf_hi(unsigned u) { return __uint_as_float(u & 0xffff0000u); }
; __device__ __forceinline__ unsigned pk_bf16(float lo, float hi) { const f32x2 v = {lo, hi}; const bf16x2_t b = __builtin_convertvector(v, bf16x2_t); return __builtin_bit_cast(unsigned, b); }
;     __device__ __forceinline__ void operator()(const f32x4 (&acc)[2][2][4][2], const pg8::Unit& u, int wr, int wc, int fr, int fq) const {
;     ...
;                     for (int bj = 0; bj < 2; ++bj)
; #pragma unroll
;                         for (int n = 0; n < 2; ++n) { const u32x2 w = *(const u32x2*)(XB + off + bj * 128 + n * 16); r4[bj][n] = (f32x4){bf_lo(w.x), bf_hi(w.x), bf_lo(w.y), bf_hi(w.y)}; }
;                 }
; #pragma unroll
;                 for (int bj = 0; bj < 2; ++bj)
; #pragma unroll
;                     for (int n = 0; n < 2; ++n) { const f32x4 x4 = r4[bj][n] + acc[ai][bj][m][n];
;                         q += (x4[0] * x4[0] + x4[1] * x4[1]) + (x4[2] * x4[2] + x4[3] * x4[3]);
;                         u32x2 w; w.x = pk_bf16(x4[0], x4[1]); w.y = pk_bf16(x4[2], x4[3]); *(u32x2*)(XB + off + bj * 128 + n * 16) = w; }
;                 q += __shfl_xor(q, 16); q += __shfl_xor(q, 32);
;                 if (fq == 0) ssq[(size_t)row * 16 + u.pn * 4 + wc] = q;
	v_permlane16_swap_b32_e32 v236, v238
	v_permlane16_swap_b32_e32 v237, v239
	v_permlane16_swap_b32_e32 v240, v242
	v_permlane16_swap_b32_e32 v241, v243
	v_lshlrev_b32_e32 v166, 16, v236
	v_and_b32_e32 v167, 0xffff0000, v236
	v_lshlrev_b32_e32 v168, 16, v237
	v_and_b32_e32 v169, 0xffff0000, v237
	v_lshlrev_b32_e32 v170, 16, v238
	v_and_b32_e32 v171, 0xffff0000, v238
	v_lshlrev_b32_e32 v172, 16, v239
	v_and_b32_e32 v173, 0xffff0000, v239
	v_lshlrev_b32_e32 v174, 16, v240
	v_and_b32_e32 v175, 0xffff0000, v240
	v_lshlrev_b32_e32 v176, 16, v241
	v_and_b32_e32 v177, 0xffff0000, v241
	v_lshlrev_b32_e32 v178, 16, v242
	v_and_b32_e32 v179, 0xffff0000, v242
	v_lshlrev_b32_e32 v180, 16, v243
	v_and_b32_e32 v181, 0xffff0000, v243
	v_pk_add_f32 v[62:63], v[62:63], v[166:167]
	v_pk_add_f32 v[64:65], v[64:65], v[168:169]
	v_pk_add_f32 v[58:59], v[58:59], v[170:171]
	v_pk_add_f32 v[60:61], v[60:61], v[172:173]
	v_pk_add_f32 v[54:55], v[54:55], v[174:175]
	v_pk_add_f32 v[56:57], v[56:57], v[176:177]
	v_pk_add_f32 v[50:51], v[50:51], v[178:179]
	v_pk_add_f32 v[52:53], v[52:53], v[180:181]
	v_cvt_pk_bf16_f32 v166, v62, v63
	v_cvt_pk_bf16_f32 v167, v64, v65
	v_cvt_pk_bf16_f32 v168, v58, v59
	v_cvt_pk_bf16_f32 v169, v60, v61
	v_cvt_pk_bf16_f32 v170, v54, v55
	v_cvt_pk_bf16_f32 v171, v56, v57
	v_cvt_pk_bf16_f32 v172, v50, v51
	v_cvt_pk_bf16_f32 v173, v52, v53
	v_mul_f32_e32 v174, v62, v62
	v_mul_f32_e32 v175, v58, v58
	v_mul_f32_e32 v176, v54, v54
	v_mul_f32_e32 v177, v50, v50
	v_fmac_f32_e32 v174, v63, v63
	v_fmac_f32_e32 v175, v59, v59
	v_fmac_f32_e32 v176, v55, v55
	v_fmac_f32_e32 v177, v51, v51
	v_fmac_f32_e32 v174, v64, v64
	v_fmac_f32_e32 v175, v60, v60
	v_fmac_f32_e32 v176, v56, v56
	v_fmac_f32_e32 v177, v52, v52
	v_fmac_f32_e32 v174, v65, v65
	v_fmac_f32_e32 v175, v61, v61
	v_fmac_f32_e32 v176, v57, v57
	v_fmac_f32_e32 v177, v53, v53
	v_add_f32_e32 v174, v174, v175
	v_add_f32_e32 v176, v176, v177
	v_add_f32_e32 v178, v174, v176
	ds_bpermute_b32 v179, v131, v178
	v_permlane16_swap_b32_e32 v166, v168
	v_permlane16_swap_b32_e32 v167, v169
	v_permlane16_swap_b32_e32 v170, v172
	v_permlane16_swap_b32_e32 v171, v173
	v_add_u32_e32 v253, 0x40000, v252
	global_store_dwordx4 v253, v[166:169], s[14:15] nt
	global_store_dwordx4 v253, v[170:173], s[14:15] offset:256 nt
	s_waitcnt lgkmcnt(0)
	v_add_f32_e32 v178, v178, v179
	ds_bpermute_b32 v179, v135, v178
	v_add_u32_e32 v189, 0x2000, v189
	s_waitcnt lgkmcnt(0)
	v_add_f32_e32 v178, v178, v179
	s_and_saveexec_b64 s[24:25], s[6:7]
	global_store_dword v189, v178, s[16:17]
	s_or_b64 exec, exec, s[24:25]
	s_waitcnt vmcnt(14)
	v_permlane16_swap_b32_e32 v244, v246
	v_permlane16_swap_b32_e32 v245, v247
	v_permlane16_swap_b32_e32 v248, v250
	v_permlane16_swap_b32_e32 v249, v251
	v_lshlrev_b32_e32 v166, 16, v244
	v_and_b32_e32 v167, 0xffff0000, v244
	v_lshlrev_b32_e32 v168, 16, v245
	v_and_b32_e32 v169, 0xffff0000, v245
	v_lshlrev_b32_e32 v170, 16, v246
	v_and_b32_e32 v171, 0xffff0000, v246
	v_lshlrev_b32_e32 v172, 16, v247
	v_and_b32_e32 v173, 0xffff0000, v247
	v_lshlrev_b32_e32 v174, 16, v248
	v_and_b32_e32 v175, 0xffff0000, v248
	v_lshlrev_b32_e32 v176, 16, v249
	v_and_b32_e32 v177, 0xffff0000, v249
	v_lshlrev_b32_e32 v178, 16, v250
	v_and_b32_e32 v179, 0xffff0000, v250
	v_lshlrev_b32_e32 v180, 16, v251
	v_and_b32_e32 v181, 0xffff0000, v251
	v_pk_add_f32 v[46:47], v[46:47], v[166:167]
	v_pk_add_f32 v[48:49], v[48:49], v[168:169]
	v_pk_add_f32 v[42:43], v[42:43], v[170:171]
	v_pk_add_f32 v[44:45], v[44:45], v[172:173]
	v_pk_add_f32 v[38:39], v[38:39], v[174:175]
	v_pk_add_f32 v[40:41], v[40:41], v[176:177]
	v_pk_add_f32 v[34:35], v[34:35], v[178:179]
	v_pk_add_f32 v[36:37], v[36:37], v[180:181]
	v_cvt_pk_bf16_f32 v166, v46, v47
	v_cvt_pk_bf16_f32 v167, v48, v49
	v_cvt_pk_bf16_f32 v168, v42, v43
	v_cvt_pk_bf16_f32 v169, v44, v45
	v_cvt_pk_bf16_f32 v170, v38, v39
	v_cvt_pk_bf16_f32 v171, v40, v41
	v_cvt_pk_bf16_f32 v172, v34, v35
	v_cvt_pk_bf16_f32 v173, v36, v37
	v_mul_f32_e32 v174, v46, v46
	v_mul_f32_e32 v175, v42, v42
	v_mul_f32_e32 v176, v38, v38
	v_mul_f32_e32 v177, v34, v34
	v_fmac_f32_e32 v174, v47, v47
	v_fmac_f32_e32 v175, v43, v43
	v_fmac_f32_e32 v176, v39, v39
	v_fmac_f32_e32 v177, v35, v35
	v_fmac_f32_e32 v174, v48, v48
	v_fmac_f32_e32 v175, v44, v44
	v_fmac_f32_e32 v176, v40, v40
	v_fmac_f32_e32 v177, v36, v36
	v_fmac_f32_e32 v174, v49, v49
	v_fmac_f32_e32 v175, v45, v45
	v_fmac_f32_e32 v176, v41, v41
	v_fmac_f32_e32 v177, v37, v37
	v_add_f32_e32 v174, v174, v175
	v_add_f32_e32 v176, v176, v177
	v_add_f32_e32 v178, v174, v176
	ds_bpermute_b32 v179, v131, v178
	v_permlane16_swap_b32_e32 v166, v168
	v_permlane16_swap_b32_e32 v167, v169
	v_permlane16_swap_b32_e32 v170, v172
	v_permlane16_swap_b32_e32 v171, v173
	v_add_u32_e32 v253, 0x48000, v252
	global_store_dwordx4 v253, v[166:169], s[14:15] nt
	global_store_dwordx4 v253, v[170:173], s[14:15] offset:256 nt
	s_waitcnt lgkmcnt(0)
	v_add_f32_e32 v178, v178, v179
	ds_bpermute_b32 v179, v135, v178
	s_waitcnt lgkmcnt(0)
	v_add_f32_e32 v178, v178, v179
	s_and_saveexec_b64 s[24:25], s[6:7]
	global_store_dword v189, v178, s[16:17] offset:1024
	s_or_b64 exec, exec, s[24:25]
	s_waitcnt vmcnt(14)
; __device__ __forceinline__ float bf_lo(unsigned u) { return __uint_as_float(u << 16); }
; __device__ __forceinline__ float bf_hi(unsigned u) { return __uint_as_float(u & 0xffff0000u); }
; __device__ __forceinline__ unsigned pk_bf16(float lo, float hi) { const f32x2 v = {lo, hi}; const bf16x2_t b = __builtin_convertvector(v, bf16x2_t); return __builtin_bit_cast(unsigned, b); }
;     __device__ __forceinline__ void operator()(const f32x4 (&acc)[2][2][4][2], const pg8::Unit& u, int wr, int wc, int fr, int fq) const {
;     ...
;                     for (int bj = 0; bj < 2; ++bj)
; #pragma unroll
;                         for (int n = 0; n < 2; ++n) { const u32x2 w = *(const u32x2*)(XB + off + bj * 128 + n * 16); r4[bj][n] = (f32x4){bf_lo(w.x), bf_hi(w.x), bf_lo(w.y), bf_hi(w.y)}; }
;                 }
; #pragma unroll
;                 for (int bj = 0; bj < 2; ++bj)
; #pragma unroll
;                     for (int n = 0; n < 2; ++n) { const f32x4 x4 = r4[bj][n] + acc[ai][bj][m][n];
;                         q += (x4[0] * x4[0] + x4[1] * x4[1]) + (x4[2] * x4[2] + x4[3] * x4[3]);
;                         u32x2 w; w.x = pk_bf16(x4[0], x4[1]); w.y = pk_bf16(x4[2], x4[3]); *(u32x2*)(XB + off + bj * 128 + n * 16) = w; }
;                 q += __shfl_xor(q, 16); q += __shfl_xor(q, 32);
;                 if (fq == 0) ssq[(size_t)row * 16 + u.pn * 4 + wc] = q;
	v_permlane16_swap_b32_e32 v204, v206
	v_permlane16_swap_b32_e32 v205, v207
	v_permlane16_swap_b32_e32 v208, v210
	v_permlane16_swap_b32_e32 v209, v211
	v_lshlrev_b32_e32 v166, 16, v204
	v_and_b32_e32 v167, 0xffff0000, v204
	v_lshlrev_b32_e32 v168, 16, v205
	v_and_b32_e32 v169, 0xffff0000, v205
	v_lshlrev_b32_e32 v170, 16, v206
	v_and_b32_e32 v171, 0xffff0000, v206
	v_lshlrev_b32_e32 v172, 16, v207
	v_and_b32_e32 v173, 0xffff0000, v207
	v_lshlrev_b32_e32 v174, 16, v208
	v_and_b32_e32 v175, 0xffff0000, v208
	v_lshlrev_b32_e32 v176, 16, v209
	v_and_b32_e32 v177, 0xffff0000, v209
	v_lshlrev_b32_e32 v178, 16, v210
	v_and_b32_e32 v179, 0xffff0000, v210
	v_lshlrev_b32_e32 v180, 16, v211
	v_and_b32_e32 v181, 0xffff0000, v211
	v_pk_add_f32 v[30:31], v[30:31], v[166:167]
	v_pk_add_f32 v[32:33], v[32:33], v[168:169]
	v_pk_add_f32 v[26:27], v[26:27], v[170:171]
	v_pk_add_f32 v[28:29], v[28:29], v[172:173]
	v_pk_add_f32 v[22:23], v[22:23], v[174:175]
	v_pk_add_f32 v[24:25], v[24:25], v[176:177]
	v_pk_add_f32 v[18:19], v[18:19], v[178:179]
	v_pk_add_f32 v[20:21], v[20:21], v[180:181]
	v_cvt_pk_bf16_f32 v166, v30, v31
	v_cvt_pk_bf16_f32 v167, v32, v33
	v_cvt_pk_bf16_f32 v168, v26, v27
	v_cvt_pk_bf16_f32 v169, v28, v29
	v_cvt_pk_bf16_f32 v170, v22, v23
	v_cvt_pk_bf16_f32 v171, v24, v25
	v_cvt_pk_bf16_f32 v172, v18, v19
	v_cvt_pk_bf16_f32 v173, v20, v21
	v_mul_f32_e32 v174, v30, v30
	v_mul_f32_e32 v175, v26, v26
	v_mul_f32_e32 v176, v22, v22
	v_mul_f32_e32 v177, v18, v18
	v_fmac_f32_e32 v174, v31, v31
	v_fmac_f32_e32 v175, v27, v27
	v_fmac_f32_e32 v176, v23, v23
	v_fmac_f32_e32 v177, v19, v19
	v_fmac_f32_e32 v174, v32, v32
	v_fmac_f32_e32 v175, v28, v28
	v_fmac_f32_e32 v176, v24, v24
	v_fmac_f32_e32 v177, v20, v20
	v_fmac_f32_e32 v174, v33, v33
	v_fmac_f32_e32 v175, v29, v29
	v_fmac_f32_e32 v176, v25, v25
	v_fmac_f32_e32 v177, v21, v21
	v_add_f32_e32 v174, v174, v175
	v_add_f32_e32 v176, v176, v177
	v_add_f32_e32 v178, v174, v176
	ds_bpermute_b32 v179, v131, v178
	v_permlane16_swap_b32_e32 v166, v168
	v_permlane16_swap_b32_e32 v167, v169
	v_permlane16_swap_b32_e32 v170, v172
	v_permlane16_swap_b32_e32 v171, v173
	v_add_u32_e32 v253, 0x50000, v252
	global_store_dwordx4 v253, v[166:169], s[14:15] nt
	global_store_dwordx4 v253, v[170:173], s[14:15] offset:256 nt
	s_waitcnt lgkmcnt(0)
	v_add_f32_e32 v178, v178, v179
	ds_bpermute_b32 v179, v135, v178
	s_waitcnt lgkmcnt(0)
	v_add_f32_e32 v178, v178, v179
	s_and_saveexec_b64 s[24:25], s[6:7]
	global_store_dword v189, v178, s[16:17] offset:2048
	s_or_b64 exec, exec, s[24:25]
	s_waitcnt vmcnt(12)
	v_permlane16_swap_b32_e32 v212, v214
	v_permlane16_swap_b32_e32 v213, v215
	v_permlane16_swap_b32_e32 v216, v218
	v_permlane16_swap_b32_e32 v217, v219
	v_lshlrev_b32_e32 v166, 16, v212
	v_and_b32_e32 v167, 0xffff0000, v212
	v_lshlrev_b32_e32 v168, 16, v213
	v_and_b32_e32 v169, 0xffff0000, v213
	v_lshlrev_b32_e32 v170, 16, v214
	v_and_b32_e32 v171, 0xffff0000, v214
	v_lshlrev_b32_e32 v172, 16, v215
	v_and_b32_e32 v173, 0xffff0000, v215
	v_lshlrev_b32_e32 v174, 16, v216
	v_and_b32_e32 v175, 0xffff0000, v216
	v_lshlrev_b32_e32 v176, 16, v217
	v_and_b32_e32 v177, 0xffff0000, v217
	v_lshlrev_b32_e32 v178, 16, v218
	v_and_b32_e32 v179, 0xffff0000, v218
	v_lshlrev_b32_e32 v180, 16, v219
	v_and_b32_e32 v181, 0xffff0000, v219
	v_pk_add_f32 v[14:15], v[14:15], v[166:167]
	v_pk_add_f32 v[16:17], v[16:17], v[168:169]
	v_pk_add_f32 v[10:11], v[10:11], v[170:171]
	v_pk_add_f32 v[12:13], v[12:13], v[172:173]
	v_pk_add_f32 v[6:7], v[6:7], v[174:175]
	v_pk_add_f32 v[8:9], v[8:9], v[176:177]
	v_pk_add_f32 v[2:3], v[2:3], v[178:179]
	v_pk_add_f32 v[4:5], v[4:5], v[180:181]
	v_cvt_pk_bf16_f32 v166, v14, v15
	v_cvt_pk_bf16_f32 v167, v16, v17
	v_cvt_pk_bf16_f32 v168, v10, v11
	v_cvt_pk_bf16_f32 v169, v12, v13
	v_cvt_pk_bf16_f32 v170, v6, v7
	v_cvt_pk_bf16_f32 v171, v8, v9
	v_cvt_pk_bf16_f32 v172, v2, v3
	v_cvt_pk_bf16_f32 v173, v4, v5
	v_mul_f32_e32 v174, v14, v14
	v_mul_f32_e32 v175, v10, v10
	v_mul_f32_e32 v176, v6, v6
	v_mul_f32_e32 v177, v2, v2
	v_fmac_f32_e32 v174, v15, v15
	v_fmac_f32_e32 v175, v11, v11
	v_fmac_f32_e32 v176, v7, v7
	v_fmac_f32_e32 v177, v3, v3
	v_fmac_f32_e32 v174, v16, v16
	v_fmac_f32_e32 v175, v12, v12
	v_fmac_f32_e32 v176, v8, v8
	v_fmac_f32_e32 v177, v4, v4
	v_fmac_f32_e32 v174, v17, v17
	v_fmac_f32_e32 v175, v13, v13
	v_fmac_f32_e32 v176, v9, v9
	v_fmac_f32_e32 v177, v5, v5
	v_add_f32_e32 v174, v174, v175
	v_add_f32_e32 v176, v176, v177
	v_add_f32_e32 v178, v174, v176
	ds_bpermute_b32 v179, v131, v178
	v_permlane16_swap_b32_e32 v166, v168
	v_permlane16_swap_b32_e32 v167, v169
	v_permlane16_swap_b32_e32 v170, v172
	v_permlane16_swap_b32_e32 v171, v173
	v_add_u32_e32 v253, 0x58000, v252
	global_store_dwordx4 v253, v[166:169], s[14:15] nt
	global_store_dwordx4 v253, v[170:173], s[14:15] offset:256 nt
	s_waitcnt lgkmcnt(0)
	v_add_f32_e32 v178, v178, v179
	ds_bpermute_b32 v179, v135, v178
	s_waitcnt lgkmcnt(0)
	v_add_f32_e32 v178, v178, v179
	s_and_saveexec_b64 s[24:25], s[6:7]
	global_store_dword v189, v178, s[16:17] offset:3072
	s_or_b64 exec, exec, s[24:25]
